# baseline (speedup 1.0000x reference)
.LBB0_1:
	v_readlane_b32 s0, v255, 0
	v_readlane_b32 s1, v255, 1
	s_add_u32 s86, s0, 0xe8
	v_and_b32_e32 v131, 0x3ff, v0
	s_addc_u32 s87, s1, 0
	s_load_dword s83, s[0:1], 0xe8
	v_cmp_eq_u32_e64 s[0:1], 0, v131
	v_and_b32_e32 v0, 0x3fffffff, v0
	s_mov_b32 s73, s2
	v_writelane_b32 v255, s0, 4
	s_mov_b32 s35, 0
	v_mov_b32_e32 v129, 0
	v_writelane_b32 v255, s1, 5
	s_and_b32 s0, s2, 7
	s_xor_b32 s1, s0, 7
	v_writelane_b32 v255, s1, 6
	v_cmp_eq_u32_e64 s[2:3], 0, v0
	s_lshl_b32 s0, s0, 6
	s_lshl_b32 s0, s0, 2
	v_writelane_b32 v255, s2, 7
	v_mov_b32_e32 v130, 0x358637bd
	s_mov_b32 s89, 0x800000
	v_writelane_b32 v255, s3, 8
	v_writelane_b32 v255, s0, 9
	s_movk_i32 s34, 0x2000
	v_readlane_b32 s0, v255, 2
	v_readlane_b32 s1, v255, 3
	v_writelane_b32 v255, s73, 10
	v_writelane_b32 v255, s86, 11
	s_mov_b64 s[44:45], 0x80
	s_mov_b32 s33, 0x42ce8ed0
	s_mov_b32 s90, 0xc2b17218
	s_mov_b32 s92, 0x3f2aaaab
	v_mov_b32_e32 v174, 0x3ecc95a3
	s_mov_b32 s93, 0x3f317218
	s_mov_b32 s30, 0x33800000
	s_movk_i32 s31, 0x5800
	v_mov_b32_e32 v175, 0x7f800000
	v_mov_b32_e32 v176, 0xff800000
	v_mov_b32_e32 v254, 0xfffff500
	v_mov_b32_e32 v177, 0x80
	s_mov_b32 s10, s0
	s_mov_b64 s[48:49], 0x40080
	s_mov_b64 s[50:51], 0x60080
	s_mov_b64 s[52:53], 0x100
	s_mov_b64 s[54:55], 0x20100
	s_mov_b64 s[56:57], 0x40100
	s_mov_b64 s[58:59], 0x60100
	s_mov_b64 s[60:61], 0x180
	s_mov_b64 s[62:63], 0x20180
	s_mov_b64 s[64:65], 0x40180
	s_mov_b64 s[66:67], 0x60180
	s_mov_b32 s72, 0xbfb8aa3b
	s_mov_b64 s[94:95], 0x58100
	s_mov_b64 s[96:97], 0xb0100
	s_mov_b64 s[74:75], 0x108100
	s_mov_b64 s[20:21], 0x58180
	s_mov_b64 s[4:5], 0x200
	s_mov_b32 s82, 0x3e38aa3b
	s_mov_b32 s88, 0x3dd2d3e7
	s_mov_b64 s[84:85], 0x800
	v_writelane_b32 v255, s87, 12
	s_mov_b32 s100, 0
	s_mov_b32 s101, 0
	s_branch .LBB0_6

.LBB0_2677:
	s_cmp_lg_u32 s100, 0
	s_cbranch_scc1 .Lrb_second
	s_bitcmp1_b32 0x22, s2
	s_cbranch_scc0 .Lrb_none
	s_mov_b32 s100, 1
	s_mov_b32 s10, s2
	s_branch .Lrb_none
.Lrb_second:
	s_mov_b32 s100, 0
	s_add_i32 s101, s101, 1

.LBB0_2681:
	s_or_b64 exec, exec, s[8:9]
	v_readlane_b32 s8, v255, 13
	v_readlane_b32 s6, v255, 6
	v_readlane_b32 s9, v255, 14
	s_add_i32 s6, s8, s6
	v_readlane_b32 s8, v255, 2
	v_readlane_b32 s7, v255, 17
	s_lshr_b32 s6, s6, 3
	s_sub_i32 s11, s7, s8
	s_add_i32 s11, s11, s101
	s_waitcnt vmcnt(0)
	v_readfirstlane_b32 s7, v1
	s_mul_i32 s6, s6, s11
	v_readlane_b32 s9, v255, 3
	v_add3_u32 v0, s7, v0, 1
	v_cmp_eq_u32_e32 vcc, s6, v0
	s_and_saveexec_b64 s[6:7], vcc
	s_cbranch_execz .LBB0_2684
	s_mov_b64 s[8:9], exec
	v_mbcnt_lo_u32_b32 v0, s8, 0
	v_mbcnt_hi_u32_b32 v0, s9, v0
	v_cmp_eq_u32_e32 vcc, 0, v0
	s_and_b64 s[12:13], exec, vcc
	s_mov_b64 exec, s[12:13]
	s_cbranch_execz .LBB0_2684
	s_bcnt1_i32_b64 s8, s[8:9]
	v_mov_b32_e32 v0, s8
	global_atomic_add v129, v0, s[2:3]
